# band-attn: counted vmcnt, unconditional K/V prefetch (2-deep prefetch restored)
# speedup vs baseline: 1.0093x; 1.0093x over previous
.LBB0_1041:
	s_or_b64 exec, exec, s[0:1]
	s_ashr_i32 s0, s3, 5
	s_add_i32 s0, s0, s4
	s_and_b32 s8, s5, 15
	s_ashr_i32 s1, s0, 31
	s_lshl_b64 s[28:29], s[0:1], 12
	s_lshl_b32 s1, s8, 8
	s_lshl_b32 s11, s8, 2
	s_or_b32 s3, s28, s1
	s_add_u32 s22, s3, s14
	s_addc_u32 s23, s29, s20
	s_mul_i32 s3, s23, 0x1400
	s_mul_hi_u32 s4, s22, 0x1400
	s_add_i32 s4, s4, s3
	s_mul_i32 s3, s22, 0x1400
	s_add_u32 s5, s60, s3
	s_addc_u32 s4, s61, s4
	s_lshl_b32 s2, s2, 6
	s_ashr_i32 s3, s2, 31
	s_lshl_b64 s[24:25], s[2:3], 1
	s_add_u32 s2, s5, s24
	s_addc_u32 s3, s4, s25
	s_add_u32 s4, s94, s24
	s_addc_u32 s5, s19, s25
	s_add_u32 s6, s31, s24
	s_addc_u32 s7, s33, s25
	s_add_i32 s9, s11, -8
	s_cmp_gt_u32 s8, 1
	s_cselect_b32 s30, s9, 0
	v_lshl_add_u64 v[0:1], s[2:3], 0, v[152:153]
	v_mov_b32_e32 v131, v153
	s_lshl_b32 s8, s30, 6
	v_lshl_add_u64 v[8:9], v[0:1], 0, v[130:131]
	s_mov_b64 s[2:3], 0x14000
	s_ashr_i32 s9, s8, 31
	v_lshl_add_u64 v[32:33], s[28:29], 0, v[114:115]
	v_lshl_add_u64 v[12:13], v[8:9], 0, s[2:3]
	s_mov_b32 s2, 0x14000
	v_lshl_add_u64 v[10:11], v[32:33], 0, s[8:9]
	global_load_dwordx4 v[0:3], v[8:9], off
	global_load_dwordx4 v[4:7], v[8:9], off offset:64
	v_add_co_u32_e32 v8, vcc, s2, v8
	v_mad_u64_u32 v[14:15], s[2:3], v10, s40, 0
	v_mad_i32_i24 v11, v11, s40, v15
	v_or_b32_e32 v10, v14, v112
	v_lshlrev_b64 v[10:11], 1, v[10:11]
	v_addc_co_u32_e32 v9, vcc, 0, v9, vcc
	v_lshl_add_u64 v[14:15], s[4:5], 0, v[10:11]
	v_lshl_add_u64 v[10:11], s[6:7], 0, v[10:11]
	global_load_dwordx4 v[16:19], v[14:15], off
	global_load_dwordx4 v[20:23], v[10:11], off
	s_nop 0
	global_load_dwordx4 v[8:11], v[8:9], off
	s_nop 0
	global_load_dwordx4 v[12:15], v[12:13], off offset:64
	s_add_i32 s2, s11, 4
	s_or_b32 s3, s30, 1
	s_cmp_ge_i32 s3, s2
	s_waitcnt vmcnt(3)
	v_mov_b64_e32 v[26:27], v[18:19]
	s_waitcnt vmcnt(2)
	v_mov_b64_e32 v[30:31], v[22:23]
	v_mov_b64_e32 v[28:29], v[20:21]
	v_mov_b64_e32 v[24:25], v[16:17]
	s_lshl_b32 s28, s3, 6
	s_ashr_i32 s29, s28, 31
	v_lshl_add_u64 v[24:25], v[32:33], 0, s[28:29]
	v_mad_u64_u32 v[26:27], s[28:29], v24, s40, 0
	v_mad_i32_i24 v25, v25, s40, v27
	v_or_b32_e32 v24, v26, v112
	v_lshlrev_b64 v[24:25], 1, v[24:25]
	v_lshl_add_u64 v[26:27], s[4:5], 0, v[24:25]
	v_lshl_add_u64 v[28:29], s[6:7], 0, v[24:25]
	global_load_dwordx4 v[24:27], v[26:27], off
	s_nop 0
	global_load_dwordx4 v[28:31], v[28:29], off

.LBB0_1044:
	s_add_i32 s29, s30, 2
	s_cmp_ge_i32 s29, s2
	s_cselect_b64 s[0:1], -1, 0
	s_and_b64 vcc, exec, s[0:1]
	s_waitcnt vmcnt(3)
	ds_write_b128 v123, v[16:19]
	s_waitcnt vmcnt(2)
	ds_write_b128 v123, v[20:23] offset:18432
	s_waitcnt lgkmcnt(0)
	s_barrier
	v_add_co_u32_e32 v20, vcc, 0xfffb0000, v140
	s_nop 1
	v_addc_co_u32_e32 v21, vcc, -1, v141, vcc
	global_load_dwordx4 v[16:19], v[20:21], off offset:-1536
	s_nop 0
	global_load_dwordx4 v[20:23], v[20:21], off
.LBB0_1046:
	s_cmp_lt_i32 s30, s27
	s_cselect_b64 s[4:5], -1, 0
	s_cmp_gt_i32 s30, s3
	s_cselect_b64 s[6:7], -1, 0
	s_or_b64 s[4:5], s[4:5], s[6:7]
	s_and_b64 vcc, exec, s[4:5]
	s_cbranch_vccnz .LBB0_1056
	ds_read_b128 v[64:67], v125
	ds_read_b128 v[72:75], v125 offset:64
	s_add_i32 s4, s28, s30
	s_add_i32 s4, s4, 8
	s_cmp_lt_i32 s4, 6
	s_cselect_b64 s[4:5], -1, 0
	s_mov_b64 s[8:9], -1
	s_and_b64 vcc, exec, s[4:5]
	s_waitcnt lgkmcnt(1)
	v_mfma_f32_16x16x32_bf16 v[68:71], v[64:67], v[0:3], 0
	ds_read_b128 v[76:79], v125 offset:4672
	ds_read_b128 v[80:83], v125 offset:6976
	v_mfma_f32_16x16x32_bf16 v[64:67], v[64:67], v[8:11], 0
	s_waitcnt lgkmcnt(2)
	v_mfma_f32_16x16x32_bf16 v[84:87], v[72:75], v[12:15], v[64:67]
	v_mfma_f32_16x16x32_bf16 v[108:111], v[72:75], v[4:7], v[68:71]
	s_nop 4
	ds_read_b128 v[64:67], v125 offset:2304
	ds_read_b128 v[72:75], v125 offset:2368
	s_waitcnt lgkmcnt(1)
	v_mfma_f32_16x16x32_bf16 v[68:71], v[64:67], v[0:3], 0
	v_mfma_f32_16x16x32_bf16 v[64:67], v[64:67], v[8:11], 0
	s_waitcnt lgkmcnt(0)
	v_mfma_f32_16x16x32_bf16 v[104:107], v[72:75], v[4:7], v[68:71]
	v_mfma_f32_16x16x32_bf16 v[72:75], v[72:75], v[12:15], v[64:67]
	s_nop 4
	ds_read_b128 v[64:67], v125 offset:4608
	s_waitcnt lgkmcnt(0)
	v_mfma_f32_16x16x32_bf16 v[68:71], v[64:67], v[0:3], 0
	v_mfma_f32_16x16x32_bf16 v[64:67], v[64:67], v[8:11], 0
	v_mfma_f32_16x16x32_bf16 v[100:103], v[76:79], v[4:7], v[68:71]
	v_mfma_f32_16x16x32_bf16 v[68:71], v[76:79], v[12:15], v[64:67]
	s_nop 5
	ds_read_b128 v[64:67], v125 offset:6912
	s_waitcnt lgkmcnt(0)
	v_mfma_f32_16x16x32_bf16 v[76:79], v[64:67], v[0:3], 0
	v_mfma_f32_16x16x32_bf16 v[64:67], v[64:67], v[8:11], 0
	v_mfma_f32_16x16x32_bf16 v[96:99], v[80:83], v[4:7], v[76:79]
	v_mfma_f32_16x16x32_bf16 v[64:67], v[80:83], v[12:15], v[64:67]
	s_cbranch_vccz .LBB0_1072
	s_nop 3
	v_max_f32_e32 v77, v111, v111
	v_max_f32_e32 v78, v110, v110
	v_max_f32_e32 v77, v78, v77
	v_max_f32_e32 v78, v107, v107
	v_max_f32_e32 v79, v106, v106
	v_max_f32_e32 v78, v79, v78
	v_max3_f32 v77, v108, v109, v77
	v_max3_f32 v78, v104, v105, v78
	v_max3_f32 v77, v77, s95, v78
	v_max_f32_e32 v78, v103, v103
	v_max_f32_e32 v79, v102, v102
	v_max_f32_e32 v78, v79, v78
	v_max_f32_e32 v79, v99, v99
	v_max_f32_e32 v80, v98, v98
	v_max_f32_e32 v79, v80, v79
	v_max3_f32 v78, v100, v101, v78
	v_max3_f32 v79, v96, v97, v79
	v_max3_f32 v77, v77, v78, v79
	v_mov_b32_e32 v78, v77
	s_nop 1
	v_permlane16_swap_b32_e32 v77, v78
	v_max_f32_e32 v78, v78, v78
	v_max_f32_e32 v77, v77, v77
	ds_read_b32 v76, v153 offset:37628
	v_max_f32_e32 v77, v77, v78
	v_mov_b32_e32 v78, v77
	s_nop 1
	v_permlane32_swap_b32_e32 v77, v78
	v_max_f32_e32 v78, v78, v78
	v_max_f32_e32 v77, v77, v77
	v_max_f32_e32 v77, v77, v78
	s_waitcnt lgkmcnt(0)
	v_fmamk_f32 v77, v77, 0x3e38aa3b, v76
	v_sub_f32_e32 v78, v77, v139
	v_cmp_ge_f32_e32 vcc, s97, v78
	v_max_f32_e32 v78, v139, v139
	v_max_f32_e32 v77, v78, v77
	s_cmp_lg_u64 vcc, exec
	v_sub_f32_e32 v78, v139, v77
	s_cselect_b64 s[6:7], -1, 0
	v_exp_f32_e32 v78, v78
	v_cndmask_b32_e64 v145, v139, v77, s[6:7]
	v_sub_f32_e32 v95, v76, v145
	v_fmamk_f32 v76, v108, 0x3e38aa3b, v95
	v_exp_f32_e32 v76, v76
	v_fmamk_f32 v77, v109, 0x3e38aa3b, v95
	v_cndmask_b32_e64 v142, 1.0, v78, s[6:7]
	v_exp_f32_e32 v77, v77
	v_fmamk_f32 v78, v110, 0x3e38aa3b, v95
	v_exp_f32_e32 v78, v78
	v_fmamk_f32 v79, v111, 0x3e38aa3b, v95
	v_exp_f32_e32 v79, v79
	v_add_f32_e32 v80, 0, v76
	v_add_f32_e32 v80, v77, v80
	v_add_f32_e32 v80, v78, v80
	v_add_f32_e32 v88, v79, v80
	v_fmamk_f32 v80, v104, 0x3e38aa3b, v95
	v_exp_f32_e32 v80, v80
	v_fmamk_f32 v81, v105, 0x3e38aa3b, v95
	v_exp_f32_e32 v81, v81
	v_fmamk_f32 v82, v106, 0x3e38aa3b, v95
	v_exp_f32_e32 v82, v82
	v_fmamk_f32 v83, v107, 0x3e38aa3b, v95
	v_exp_f32_e32 v83, v83
	v_add_f32_e32 v88, v80, v88
	v_add_f32_e32 v88, v81, v88
	v_add_f32_e32 v88, v82, v88
	v_add_f32_e32 v92, v83, v88
	v_fmamk_f32 v88, v100, 0x3e38aa3b, v95
	v_exp_f32_e32 v88, v88
	v_fmamk_f32 v89, v101, 0x3e38aa3b, v95
	v_exp_f32_e32 v89, v89
	v_fmamk_f32 v90, v102, 0x3e38aa3b, v95
	v_exp_f32_e32 v90, v90
	v_fmamk_f32 v91, v103, 0x3e38aa3b, v95
	v_exp_f32_e32 v91, v91
	v_add_f32_e32 v92, v88, v92
	v_add_f32_e32 v92, v89, v92
	v_add_f32_e32 v92, v90, v92
	v_add_f32_e32 v146, v91, v92
	v_fmamk_f32 v92, v96, 0x3e38aa3b, v95
	v_exp_f32_e32 v92, v92
	v_fmamk_f32 v93, v97, 0x3e38aa3b, v95
	v_exp_f32_e32 v93, v93
	v_fmamk_f32 v94, v98, 0x3e38aa3b, v95
	v_exp_f32_e32 v94, v94
	v_fmac_f32_e32 v95, 0x3e38aa3b, v99
	v_exp_f32_e32 v95, v95
	v_add_f32_e32 v146, v92, v146
	v_add_f32_e32 v146, v93, v146
	v_add_f32_e32 v146, v94, v146
	v_add_f32_e32 v147, v95, v146
	s_cbranch_execz .LBB0_1073

.LBB0_1057:
	s_add_i32 s5, s30, 3
	s_cmp_ge_i32 s5, s2
	s_waitcnt vmcnt(3)
	ds_write_b128 v123, v[24:27] offset:9216
	s_waitcnt vmcnt(2)
	ds_write_b128 v123, v[28:31] offset:27648
	s_waitcnt lgkmcnt(0)
	s_barrier
	global_load_dwordx4 v[24:27], v[140:141], off offset:-1536
	global_load_dwordx4 v[28:31], v[140:141], off
